# v68 + P3 epilogue with gain / row-rms / residual loads issued up front (counted waits) instead of a load-wait-compute-store ladder
# baseline (speedup 1.0000x reference)
.LBB0_262:
	v_lshl_or_b32 v156, s62, 8, v170
	v_lshl_add_u32 v157, s0, 8, v168
	v_lshlrev_b32_e32 v159, 2, v156
	v_lshl_add_u32 v158, v157, 10, v156
	v_lshlrev_b32_e32 v158, 1, v158
	v_lshlrev_b32_e32 v160, 2, v157
	global_load_dwordx4 v[176:179], v159, s[38:39]
	global_load_dwordx4 v[180:183], v159, s[38:39] offset:16
	global_load_dwordx4 v[184:187], v159, s[38:39] offset:512
	global_load_dwordx4 v[188:191], v159, s[38:39] offset:528
	global_load_dword v128, v160, s[66:67] offset:0
	global_load_dword v129, v160, s[66:67] offset:64
	global_load_dword v130, v160, s[66:67] offset:128
	global_load_dword v131, v160, s[66:67] offset:192
	global_load_dword v132, v160, s[66:67] offset:512
	global_load_dword v133, v160, s[66:67] offset:576
	global_load_dword v134, v160, s[66:67] offset:640
	global_load_dword v135, v160, s[66:67] offset:704
	v_mov_b32_e32 v139, v158
	global_load_dwordx4 v[206:209], v139, s[48:49]
	global_load_dwordx4 v[210:213], v139, s[48:49] offset:256
	v_add_u32_e32 v139, 0x8000, v158
	global_load_dwordx4 v[214:217], v139, s[48:49]
	global_load_dwordx4 v[218:221], v139, s[48:49] offset:256
	v_add_u32_e32 v139, 0x10000, v158
	global_load_dwordx4 v[222:225], v139, s[48:49]
	global_load_dwordx4 v[226:229], v139, s[48:49] offset:256
	v_add_u32_e32 v139, 0x18000, v158
	global_load_dwordx4 v[230:233], v139, s[48:49]
	global_load_dwordx4 v[234:237], v139, s[48:49] offset:256
	s_lshl_b32 s12, s62, 4
	s_lshl_b32 s13, s87, 2
	s_add_i32 s12, s12, s13
	v_lshl_add_u32 v161, v157, 6, s12
	v_add_u32_e32 v162, 0x2000, v161
	v_xor_b32_e32 v163, 16, v174
	v_lshlrev_b32_e32 v163, 2, v163
	v_xor_b32_e32 v164, 32, v174
	v_lshlrev_b32_e32 v164, 2, v164
	s_waitcnt vmcnt(16)
	v_div_scale_f32 v165, s[12:13], v176, v176, 1.0
	v_div_scale_f32 v166, vcc, 1.0, v176, 1.0
	v_rcp_f32_e32 v167, v165
	s_nop 0
	v_fma_f32 v175, -v165, v167, 1.0
	v_fmac_f32_e32 v167, v175, v167
	v_mul_f32_e32 v197, v166, v167
	v_fma_f32 v175, -v165, v197, v166
	v_fmac_f32_e32 v197, v175, v167
	v_fma_f32 v165, -v165, v197, v166
	v_div_fmas_f32 v165, v165, v167, v197
	v_div_fixup_f32 v176, v165, v176, 1.0
	v_div_scale_f32 v165, s[12:13], v177, v177, 1.0
	v_div_scale_f32 v166, vcc, 1.0, v177, 1.0
	v_rcp_f32_e32 v167, v165
	s_nop 0
	v_fma_f32 v175, -v165, v167, 1.0
	v_fmac_f32_e32 v167, v175, v167
	v_mul_f32_e32 v197, v166, v167
	v_fma_f32 v175, -v165, v197, v166
	v_fmac_f32_e32 v197, v175, v167
	v_fma_f32 v165, -v165, v197, v166
	v_div_fmas_f32 v165, v165, v167, v197
	v_div_fixup_f32 v177, v165, v177, 1.0
	v_div_scale_f32 v165, s[12:13], v178, v178, 1.0
	v_div_scale_f32 v166, vcc, 1.0, v178, 1.0
	v_rcp_f32_e32 v167, v165
	s_nop 0
	v_fma_f32 v175, -v165, v167, 1.0
	v_fmac_f32_e32 v167, v175, v167
	v_mul_f32_e32 v197, v166, v167
	v_fma_f32 v175, -v165, v197, v166
	v_fmac_f32_e32 v197, v175, v167
	v_fma_f32 v165, -v165, v197, v166
	v_div_fmas_f32 v165, v165, v167, v197
	v_div_fixup_f32 v178, v165, v178, 1.0
	v_div_scale_f32 v165, s[12:13], v179, v179, 1.0
	v_div_scale_f32 v166, vcc, 1.0, v179, 1.0
	v_rcp_f32_e32 v167, v165
	s_nop 0
	v_fma_f32 v175, -v165, v167, 1.0
	v_fmac_f32_e32 v167, v175, v167
	v_mul_f32_e32 v197, v166, v167
	v_fma_f32 v175, -v165, v197, v166
	v_fmac_f32_e32 v197, v175, v167
	v_fma_f32 v165, -v165, v197, v166
	v_div_fmas_f32 v165, v165, v167, v197
	v_div_fixup_f32 v179, v165, v179, 1.0
	v_div_scale_f32 v165, s[12:13], v180, v180, 1.0
	v_div_scale_f32 v166, vcc, 1.0, v180, 1.0
	v_rcp_f32_e32 v167, v165
	s_nop 0
	v_fma_f32 v175, -v165, v167, 1.0
	v_fmac_f32_e32 v167, v175, v167
	v_mul_f32_e32 v197, v166, v167
	v_fma_f32 v175, -v165, v197, v166
	v_fmac_f32_e32 v197, v175, v167
	v_fma_f32 v165, -v165, v197, v166
	v_div_fmas_f32 v165, v165, v167, v197
	v_div_fixup_f32 v180, v165, v180, 1.0
	v_div_scale_f32 v165, s[12:13], v181, v181, 1.0
	v_div_scale_f32 v166, vcc, 1.0, v181, 1.0
	v_rcp_f32_e32 v167, v165
	s_nop 0
	v_fma_f32 v175, -v165, v167, 1.0
	v_fmac_f32_e32 v167, v175, v167
	v_mul_f32_e32 v197, v166, v167
	v_fma_f32 v175, -v165, v197, v166
	v_fmac_f32_e32 v197, v175, v167
	v_fma_f32 v165, -v165, v197, v166
	v_div_fmas_f32 v165, v165, v167, v197
	v_div_fixup_f32 v181, v165, v181, 1.0
	v_div_scale_f32 v165, s[12:13], v182, v182, 1.0
	v_div_scale_f32 v166, vcc, 1.0, v182, 1.0
	v_rcp_f32_e32 v167, v165
	s_nop 0
	v_fma_f32 v175, -v165, v167, 1.0
	v_fmac_f32_e32 v167, v175, v167
	v_mul_f32_e32 v197, v166, v167
	v_fma_f32 v175, -v165, v197, v166
	v_fmac_f32_e32 v197, v175, v167
	v_fma_f32 v165, -v165, v197, v166
	v_div_fmas_f32 v165, v165, v167, v197
	v_div_fixup_f32 v182, v165, v182, 1.0
	v_div_scale_f32 v165, s[12:13], v183, v183, 1.0
	v_div_scale_f32 v166, vcc, 1.0, v183, 1.0
	v_rcp_f32_e32 v167, v165
	s_nop 0
	v_fma_f32 v175, -v165, v167, 1.0
	v_fmac_f32_e32 v167, v175, v167
	v_mul_f32_e32 v197, v166, v167
	v_fma_f32 v175, -v165, v197, v166
	v_fmac_f32_e32 v197, v175, v167
	v_fma_f32 v165, -v165, v197, v166
	v_div_fmas_f32 v165, v165, v167, v197
	v_div_fixup_f32 v183, v165, v183, 1.0
	v_div_scale_f32 v165, s[12:13], v184, v184, 1.0
	v_div_scale_f32 v166, vcc, 1.0, v184, 1.0
	v_rcp_f32_e32 v167, v165
	s_nop 0
	v_fma_f32 v175, -v165, v167, 1.0
	v_fmac_f32_e32 v167, v175, v167
	v_mul_f32_e32 v197, v166, v167
	v_fma_f32 v175, -v165, v197, v166
	v_fmac_f32_e32 v197, v175, v167
	v_fma_f32 v165, -v165, v197, v166
	v_div_fmas_f32 v165, v165, v167, v197
	v_div_fixup_f32 v184, v165, v184, 1.0
	v_div_scale_f32 v165, s[12:13], v185, v185, 1.0
	v_div_scale_f32 v166, vcc, 1.0, v185, 1.0
	v_rcp_f32_e32 v167, v165
	s_nop 0
	v_fma_f32 v175, -v165, v167, 1.0
	v_fmac_f32_e32 v167, v175, v167
	v_mul_f32_e32 v197, v166, v167
	v_fma_f32 v175, -v165, v197, v166
	v_fmac_f32_e32 v197, v175, v167
	v_fma_f32 v165, -v165, v197, v166
	v_div_fmas_f32 v165, v165, v167, v197
	v_div_fixup_f32 v185, v165, v185, 1.0
	v_div_scale_f32 v165, s[12:13], v186, v186, 1.0
	v_div_scale_f32 v166, vcc, 1.0, v186, 1.0
	v_rcp_f32_e32 v167, v165
	s_nop 0
	v_fma_f32 v175, -v165, v167, 1.0
	v_fmac_f32_e32 v167, v175, v167
	v_mul_f32_e32 v197, v166, v167
	v_fma_f32 v175, -v165, v197, v166
	v_fmac_f32_e32 v197, v175, v167
	v_fma_f32 v165, -v165, v197, v166
	v_div_fmas_f32 v165, v165, v167, v197
	v_div_fixup_f32 v186, v165, v186, 1.0
	v_div_scale_f32 v165, s[12:13], v187, v187, 1.0
	v_div_scale_f32 v166, vcc, 1.0, v187, 1.0
	v_rcp_f32_e32 v167, v165
	s_nop 0
	v_fma_f32 v175, -v165, v167, 1.0
	v_fmac_f32_e32 v167, v175, v167
	v_mul_f32_e32 v197, v166, v167
	v_fma_f32 v175, -v165, v197, v166
	v_fmac_f32_e32 v197, v175, v167
	v_fma_f32 v165, -v165, v197, v166
	v_div_fmas_f32 v165, v165, v167, v197
	v_div_fixup_f32 v187, v165, v187, 1.0
	v_div_scale_f32 v165, s[12:13], v188, v188, 1.0
	v_div_scale_f32 v166, vcc, 1.0, v188, 1.0
	v_rcp_f32_e32 v167, v165
	s_nop 0
	v_fma_f32 v175, -v165, v167, 1.0
	v_fmac_f32_e32 v167, v175, v167
	v_mul_f32_e32 v197, v166, v167
	v_fma_f32 v175, -v165, v197, v166
	v_fmac_f32_e32 v197, v175, v167
	v_fma_f32 v165, -v165, v197, v166
	v_div_fmas_f32 v165, v165, v167, v197
	v_div_fixup_f32 v188, v165, v188, 1.0
	v_div_scale_f32 v165, s[12:13], v189, v189, 1.0
	v_div_scale_f32 v166, vcc, 1.0, v189, 1.0
	v_rcp_f32_e32 v167, v165
	s_nop 0
	v_fma_f32 v175, -v165, v167, 1.0
	v_fmac_f32_e32 v167, v175, v167
	v_mul_f32_e32 v197, v166, v167
	v_fma_f32 v175, -v165, v197, v166
	v_fmac_f32_e32 v197, v175, v167
	v_fma_f32 v165, -v165, v197, v166
	v_div_fmas_f32 v165, v165, v167, v197
	v_div_fixup_f32 v189, v165, v189, 1.0
	v_div_scale_f32 v165, s[12:13], v190, v190, 1.0
	v_div_scale_f32 v166, vcc, 1.0, v190, 1.0
	v_rcp_f32_e32 v167, v165
	s_nop 0
	v_fma_f32 v175, -v165, v167, 1.0
	v_fmac_f32_e32 v167, v175, v167
	v_mul_f32_e32 v197, v166, v167
	v_fma_f32 v175, -v165, v197, v166
	v_fmac_f32_e32 v197, v175, v167
	v_fma_f32 v165, -v165, v197, v166
	v_div_fmas_f32 v165, v165, v167, v197
	v_div_fixup_f32 v190, v165, v190, 1.0
	v_div_scale_f32 v165, s[12:13], v191, v191, 1.0
	v_div_scale_f32 v166, vcc, 1.0, v191, 1.0
	v_rcp_f32_e32 v167, v165
	s_nop 0
	v_fma_f32 v175, -v165, v167, 1.0
	v_fmac_f32_e32 v167, v175, v167
	v_mul_f32_e32 v197, v166, v167
	v_fma_f32 v175, -v165, v197, v166
	v_fmac_f32_e32 v197, v175, v167
	v_fma_f32 v165, -v165, v197, v166
	v_div_fmas_f32 v165, v165, v167, v197
	v_div_fixup_f32 v191, v165, v191, 1.0
	s_waitcnt vmcnt(7)
	v_mov_b32_e32 v138, v128
	v_lshlrev_b32_e32 v238, 16, v206
	v_and_b32_e32 v239, 0xffff0000, v206
	v_lshlrev_b32_e32 v206, 16, v207
	v_and_b32_e32 v207, 0xffff0000, v207
	v_lshlrev_b32_e32 v240, 16, v208
	v_and_b32_e32 v241, 0xffff0000, v208
	v_lshlrev_b32_e32 v208, 16, v209
	v_and_b32_e32 v209, 0xffff0000, v209
	v_pk_mul_f32 v[238:239], v[176:177], v[238:239]
	v_pk_mul_f32 v[206:207], v[178:179], v[206:207]
	v_pk_mul_f32 v[240:241], v[180:181], v[240:241]
	v_pk_mul_f32 v[208:209], v[182:183], v[208:209]
	v_pk_fma_f32 v[124:125], v[138:139], v[238:239], v[124:125] op_sel_hi:[0,1,1]
	v_pk_fma_f32 v[126:127], v[138:139], v[206:207], v[126:127] op_sel_hi:[0,1,1]
	v_pk_fma_f32 v[120:121], v[138:139], v[240:241], v[120:121] op_sel_hi:[0,1,1]
	v_pk_fma_f32 v[122:123], v[138:139], v[208:209], v[122:123] op_sel_hi:[0,1,1]
	v_add_u32_e32 v139, 0x40000, v158
	global_load_dwordx4 v[206:209], v139, s[48:49]
	v_mul_f32_e32 v136, v124, v124
	v_mul_f32_e32 v137, v120, v120
	v_fmac_f32_e32 v136, v125, v125
	v_fmac_f32_e32 v137, v121, v121
	v_fmac_f32_e32 v136, v126, v126
	v_fmac_f32_e32 v137, v122, v122
	v_fmac_f32_e32 v136, v127, v127
	v_fmac_f32_e32 v137, v123, v123
	v_cvt_pk_bf16_f32 v192, v124, v125
	v_cvt_pk_bf16_f32 v193, v126, v127
	v_cvt_pk_bf16_f32 v194, v120, v121
	v_cvt_pk_bf16_f32 v195, v122, v123
	v_add_f32_e32 v136, v136, v137
	v_mov_b32_e32 v127, v136
	v_mov_b32_e32 v139, v158
	global_store_dwordx4 v139, v[192:195], s[36:37]
	s_waitcnt vmcnt(8)
	v_lshlrev_b32_e32 v238, 16, v210
	v_and_b32_e32 v239, 0xffff0000, v210
	v_lshlrev_b32_e32 v210, 16, v211
	v_and_b32_e32 v211, 0xffff0000, v211
	v_lshlrev_b32_e32 v240, 16, v212
	v_and_b32_e32 v241, 0xffff0000, v212
	v_lshlrev_b32_e32 v212, 16, v213
	v_and_b32_e32 v213, 0xffff0000, v213
	v_pk_mul_f32 v[238:239], v[184:185], v[238:239]
	v_pk_mul_f32 v[210:211], v[186:187], v[210:211]
	v_pk_mul_f32 v[240:241], v[188:189], v[240:241]
	v_pk_mul_f32 v[212:213], v[190:191], v[212:213]
	v_pk_fma_f32 v[116:117], v[138:139], v[238:239], v[116:117] op_sel_hi:[0,1,1]
	v_pk_fma_f32 v[118:119], v[138:139], v[210:211], v[118:119] op_sel_hi:[0,1,1]
	v_pk_fma_f32 v[112:113], v[138:139], v[240:241], v[112:113] op_sel_hi:[0,1,1]
	v_pk_fma_f32 v[114:115], v[138:139], v[212:213], v[114:115] op_sel_hi:[0,1,1]
	v_add_u32_e32 v139, 0x40000, v158
	global_load_dwordx4 v[210:213], v139, s[48:49] offset:256
	v_mul_f32_e32 v136, v116, v116
	v_mul_f32_e32 v137, v112, v112
	v_fmac_f32_e32 v136, v117, v117
	v_fmac_f32_e32 v137, v113, v113
	v_fmac_f32_e32 v136, v118, v118
	v_fmac_f32_e32 v137, v114, v114
	v_fmac_f32_e32 v136, v119, v119
	v_fmac_f32_e32 v137, v115, v115
	v_cvt_pk_bf16_f32 v198, v116, v117
	v_cvt_pk_bf16_f32 v199, v118, v119
	v_cvt_pk_bf16_f32 v200, v112, v113
	v_cvt_pk_bf16_f32 v201, v114, v115
	v_add_f32_e32 v136, v136, v137
	v_add_f32_e32 v127, v127, v136
	v_mov_b32_e32 v139, v158
	global_store_dwordx4 v139, v[198:201], s[36:37] offset:256
	s_waitcnt vmcnt(9)
	v_mov_b32_e32 v138, v129
	v_lshlrev_b32_e32 v238, 16, v214
	v_and_b32_e32 v239, 0xffff0000, v214
	v_lshlrev_b32_e32 v214, 16, v215
	v_and_b32_e32 v215, 0xffff0000, v215
	v_lshlrev_b32_e32 v240, 16, v216
	v_and_b32_e32 v241, 0xffff0000, v216
	v_lshlrev_b32_e32 v216, 16, v217
	v_and_b32_e32 v217, 0xffff0000, v217
	v_pk_mul_f32 v[238:239], v[176:177], v[238:239]
	v_pk_mul_f32 v[214:215], v[178:179], v[214:215]
	v_pk_mul_f32 v[240:241], v[180:181], v[240:241]
	v_pk_mul_f32 v[216:217], v[182:183], v[216:217]
	v_pk_fma_f32 v[108:109], v[138:139], v[238:239], v[108:109] op_sel_hi:[0,1,1]
	v_pk_fma_f32 v[110:111], v[138:139], v[214:215], v[110:111] op_sel_hi:[0,1,1]
	v_pk_fma_f32 v[104:105], v[138:139], v[240:241], v[104:105] op_sel_hi:[0,1,1]
	v_pk_fma_f32 v[106:107], v[138:139], v[216:217], v[106:107] op_sel_hi:[0,1,1]
	v_add_u32_e32 v139, 0x48000, v158
	global_load_dwordx4 v[214:217], v139, s[48:49]
	v_mul_f32_e32 v136, v108, v108
	v_mul_f32_e32 v137, v104, v104
	v_fmac_f32_e32 v136, v109, v109
	v_fmac_f32_e32 v137, v105, v105
	v_fmac_f32_e32 v136, v110, v110
	v_fmac_f32_e32 v137, v106, v106
	v_fmac_f32_e32 v136, v111, v111
	v_fmac_f32_e32 v137, v107, v107
	v_cvt_pk_bf16_f32 v192, v108, v109
	v_cvt_pk_bf16_f32 v193, v110, v111
	v_cvt_pk_bf16_f32 v194, v104, v105
	v_cvt_pk_bf16_f32 v195, v106, v107
	v_add_f32_e32 v136, v136, v137
	v_mov_b32_e32 v111, v136
	v_add_u32_e32 v139, 0x8000, v158
	global_store_dwordx4 v139, v[192:195], s[36:37]
	s_waitcnt vmcnt(10)
	v_lshlrev_b32_e32 v238, 16, v218
	v_and_b32_e32 v239, 0xffff0000, v218
	v_lshlrev_b32_e32 v218, 16, v219
	v_and_b32_e32 v219, 0xffff0000, v219
	v_lshlrev_b32_e32 v240, 16, v220
	v_and_b32_e32 v241, 0xffff0000, v220
	v_lshlrev_b32_e32 v220, 16, v221
	v_and_b32_e32 v221, 0xffff0000, v221
	v_pk_mul_f32 v[238:239], v[184:185], v[238:239]
	v_pk_mul_f32 v[218:219], v[186:187], v[218:219]
	v_pk_mul_f32 v[240:241], v[188:189], v[240:241]
	v_pk_mul_f32 v[220:221], v[190:191], v[220:221]
	v_pk_fma_f32 v[100:101], v[138:139], v[238:239], v[100:101] op_sel_hi:[0,1,1]
	v_pk_fma_f32 v[102:103], v[138:139], v[218:219], v[102:103] op_sel_hi:[0,1,1]
	v_pk_fma_f32 v[96:97], v[138:139], v[240:241], v[96:97] op_sel_hi:[0,1,1]
	v_pk_fma_f32 v[98:99], v[138:139], v[220:221], v[98:99] op_sel_hi:[0,1,1]
	v_add_u32_e32 v139, 0x48000, v158
	global_load_dwordx4 v[218:221], v139, s[48:49] offset:256
	v_mul_f32_e32 v136, v100, v100
	v_mul_f32_e32 v137, v96, v96
	v_fmac_f32_e32 v136, v101, v101
	v_fmac_f32_e32 v137, v97, v97
	v_fmac_f32_e32 v136, v102, v102
	v_fmac_f32_e32 v137, v98, v98
	v_fmac_f32_e32 v136, v103, v103
	v_fmac_f32_e32 v137, v99, v99
	v_cvt_pk_bf16_f32 v198, v100, v101
	v_cvt_pk_bf16_f32 v199, v102, v103
	v_cvt_pk_bf16_f32 v200, v96, v97
	v_cvt_pk_bf16_f32 v201, v98, v99
	v_add_f32_e32 v136, v136, v137
	v_add_f32_e32 v111, v111, v136
	v_add_u32_e32 v139, 0x8000, v158
	global_store_dwordx4 v139, v[198:201], s[36:37] offset:256
	s_waitcnt vmcnt(11)
	v_mov_b32_e32 v138, v130
	v_lshlrev_b32_e32 v238, 16, v222
	v_and_b32_e32 v239, 0xffff0000, v222
	v_lshlrev_b32_e32 v222, 16, v223
	v_and_b32_e32 v223, 0xffff0000, v223
	v_lshlrev_b32_e32 v240, 16, v224
	v_and_b32_e32 v241, 0xffff0000, v224
	v_lshlrev_b32_e32 v224, 16, v225
	v_and_b32_e32 v225, 0xffff0000, v225
	v_pk_mul_f32 v[238:239], v[176:177], v[238:239]
	v_pk_mul_f32 v[222:223], v[178:179], v[222:223]
	v_pk_mul_f32 v[240:241], v[180:181], v[240:241]
	v_pk_mul_f32 v[224:225], v[182:183], v[224:225]
	v_pk_fma_f32 v[92:93], v[138:139], v[238:239], v[92:93] op_sel_hi:[0,1,1]
	v_pk_fma_f32 v[94:95], v[138:139], v[222:223], v[94:95] op_sel_hi:[0,1,1]
	v_pk_fma_f32 v[88:89], v[138:139], v[240:241], v[88:89] op_sel_hi:[0,1,1]
	v_pk_fma_f32 v[90:91], v[138:139], v[224:225], v[90:91] op_sel_hi:[0,1,1]
	v_add_u32_e32 v139, 0x50000, v158
	global_load_dwordx4 v[222:225], v139, s[48:49]
	v_mul_f32_e32 v136, v92, v92
	v_mul_f32_e32 v137, v88, v88
	v_fmac_f32_e32 v136, v93, v93
	v_fmac_f32_e32 v137, v89, v89
	v_fmac_f32_e32 v136, v94, v94
	v_fmac_f32_e32 v137, v90, v90
	v_fmac_f32_e32 v136, v95, v95
	v_fmac_f32_e32 v137, v91, v91
	v_cvt_pk_bf16_f32 v192, v92, v93
	v_cvt_pk_bf16_f32 v193, v94, v95
	v_cvt_pk_bf16_f32 v194, v88, v89
	v_cvt_pk_bf16_f32 v195, v90, v91
	v_add_f32_e32 v136, v136, v137
	v_mov_b32_e32 v95, v136
	v_add_u32_e32 v139, 0x10000, v158
	global_store_dwordx4 v139, v[192:195], s[36:37]
	s_waitcnt vmcnt(12)
	v_lshlrev_b32_e32 v238, 16, v226
	v_and_b32_e32 v239, 0xffff0000, v226
	v_lshlrev_b32_e32 v226, 16, v227
	v_and_b32_e32 v227, 0xffff0000, v227
	v_lshlrev_b32_e32 v240, 16, v228
	v_and_b32_e32 v241, 0xffff0000, v228
	v_lshlrev_b32_e32 v228, 16, v229
	v_and_b32_e32 v229, 0xffff0000, v229
	v_pk_mul_f32 v[238:239], v[184:185], v[238:239]
	v_pk_mul_f32 v[226:227], v[186:187], v[226:227]
	v_pk_mul_f32 v[240:241], v[188:189], v[240:241]
	v_pk_mul_f32 v[228:229], v[190:191], v[228:229]
	v_pk_fma_f32 v[84:85], v[138:139], v[238:239], v[84:85] op_sel_hi:[0,1,1]
	v_pk_fma_f32 v[86:87], v[138:139], v[226:227], v[86:87] op_sel_hi:[0,1,1]
	v_pk_fma_f32 v[80:81], v[138:139], v[240:241], v[80:81] op_sel_hi:[0,1,1]
	v_pk_fma_f32 v[82:83], v[138:139], v[228:229], v[82:83] op_sel_hi:[0,1,1]
	v_add_u32_e32 v139, 0x50000, v158
	global_load_dwordx4 v[226:229], v139, s[48:49] offset:256
	v_mul_f32_e32 v136, v84, v84
	v_mul_f32_e32 v137, v80, v80
	v_fmac_f32_e32 v136, v85, v85
	v_fmac_f32_e32 v137, v81, v81
	v_fmac_f32_e32 v136, v86, v86
	v_fmac_f32_e32 v137, v82, v82
	v_fmac_f32_e32 v136, v87, v87
	v_fmac_f32_e32 v137, v83, v83
	v_cvt_pk_bf16_f32 v198, v84, v85
	v_cvt_pk_bf16_f32 v199, v86, v87
	v_cvt_pk_bf16_f32 v200, v80, v81
	v_cvt_pk_bf16_f32 v201, v82, v83
	v_add_f32_e32 v136, v136, v137
	v_add_f32_e32 v95, v95, v136
	v_add_u32_e32 v139, 0x10000, v158
	global_store_dwordx4 v139, v[198:201], s[36:37] offset:256
	s_waitcnt vmcnt(13)
	v_mov_b32_e32 v138, v131
	v_lshlrev_b32_e32 v238, 16, v230
	v_and_b32_e32 v239, 0xffff0000, v230
	v_lshlrev_b32_e32 v230, 16, v231
	v_and_b32_e32 v231, 0xffff0000, v231
	v_lshlrev_b32_e32 v240, 16, v232
	v_and_b32_e32 v241, 0xffff0000, v232
	v_lshlrev_b32_e32 v232, 16, v233
	v_and_b32_e32 v233, 0xffff0000, v233
	v_pk_mul_f32 v[238:239], v[176:177], v[238:239]
	v_pk_mul_f32 v[230:231], v[178:179], v[230:231]
	v_pk_mul_f32 v[240:241], v[180:181], v[240:241]
	v_pk_mul_f32 v[232:233], v[182:183], v[232:233]
	v_pk_fma_f32 v[76:77], v[138:139], v[238:239], v[76:77] op_sel_hi:[0,1,1]
	v_pk_fma_f32 v[78:79], v[138:139], v[230:231], v[78:79] op_sel_hi:[0,1,1]
	v_pk_fma_f32 v[72:73], v[138:139], v[240:241], v[72:73] op_sel_hi:[0,1,1]
	v_pk_fma_f32 v[74:75], v[138:139], v[232:233], v[74:75] op_sel_hi:[0,1,1]
	v_add_u32_e32 v139, 0x58000, v158
	global_load_dwordx4 v[230:233], v139, s[48:49]
	v_mul_f32_e32 v136, v76, v76
	v_mul_f32_e32 v137, v72, v72
	v_fmac_f32_e32 v136, v77, v77
	v_fmac_f32_e32 v137, v73, v73
	v_fmac_f32_e32 v136, v78, v78
	v_fmac_f32_e32 v137, v74, v74
	v_fmac_f32_e32 v136, v79, v79
	v_fmac_f32_e32 v137, v75, v75
	v_cvt_pk_bf16_f32 v192, v76, v77
	v_cvt_pk_bf16_f32 v193, v78, v79
	v_cvt_pk_bf16_f32 v194, v72, v73
	v_cvt_pk_bf16_f32 v195, v74, v75
	v_add_f32_e32 v136, v136, v137
	v_mov_b32_e32 v79, v136
	v_add_u32_e32 v139, 0x18000, v158
	global_store_dwordx4 v139, v[192:195], s[36:37]
	s_waitcnt vmcnt(14)
	v_lshlrev_b32_e32 v238, 16, v234
	v_and_b32_e32 v239, 0xffff0000, v234
	v_lshlrev_b32_e32 v234, 16, v235
	v_and_b32_e32 v235, 0xffff0000, v235
	v_lshlrev_b32_e32 v240, 16, v236
	v_and_b32_e32 v241, 0xffff0000, v236
	v_lshlrev_b32_e32 v236, 16, v237
	v_and_b32_e32 v237, 0xffff0000, v237
	v_pk_mul_f32 v[238:239], v[184:185], v[238:239]
	v_pk_mul_f32 v[234:235], v[186:187], v[234:235]
	v_pk_mul_f32 v[240:241], v[188:189], v[240:241]
	v_pk_mul_f32 v[236:237], v[190:191], v[236:237]
	v_pk_fma_f32 v[68:69], v[138:139], v[238:239], v[68:69] op_sel_hi:[0,1,1]
	v_pk_fma_f32 v[70:71], v[138:139], v[234:235], v[70:71] op_sel_hi:[0,1,1]
	v_pk_fma_f32 v[64:65], v[138:139], v[240:241], v[64:65] op_sel_hi:[0,1,1]
	v_pk_fma_f32 v[66:67], v[138:139], v[236:237], v[66:67] op_sel_hi:[0,1,1]
	v_add_u32_e32 v139, 0x58000, v158
	global_load_dwordx4 v[234:237], v139, s[48:49] offset:256
	v_mul_f32_e32 v136, v68, v68
	v_mul_f32_e32 v137, v64, v64
	v_fmac_f32_e32 v136, v69, v69
	v_fmac_f32_e32 v137, v65, v65
	v_fmac_f32_e32 v136, v70, v70
	v_fmac_f32_e32 v137, v66, v66
	v_fmac_f32_e32 v136, v71, v71
	v_fmac_f32_e32 v137, v67, v67
	v_cvt_pk_bf16_f32 v198, v68, v69
	v_cvt_pk_bf16_f32 v199, v70, v71
	v_cvt_pk_bf16_f32 v200, v64, v65
	v_cvt_pk_bf16_f32 v201, v66, v67
	v_add_f32_e32 v136, v136, v137
	v_add_f32_e32 v79, v79, v136
	v_add_u32_e32 v139, 0x18000, v158
	global_store_dwordx4 v139, v[198:201], s[36:37] offset:256
	s_waitcnt vmcnt(15)
	v_mov_b32_e32 v138, v132
	v_lshlrev_b32_e32 v238, 16, v206
	v_and_b32_e32 v239, 0xffff0000, v206
	v_lshlrev_b32_e32 v206, 16, v207
	v_and_b32_e32 v207, 0xffff0000, v207
	v_lshlrev_b32_e32 v240, 16, v208
	v_and_b32_e32 v241, 0xffff0000, v208
	v_lshlrev_b32_e32 v208, 16, v209
	v_and_b32_e32 v209, 0xffff0000, v209
	v_pk_mul_f32 v[238:239], v[176:177], v[238:239]
	v_pk_mul_f32 v[206:207], v[178:179], v[206:207]
	v_pk_mul_f32 v[240:241], v[180:181], v[240:241]
	v_pk_mul_f32 v[208:209], v[182:183], v[208:209]
	v_pk_fma_f32 v[60:61], v[138:139], v[238:239], v[60:61] op_sel_hi:[0,1,1]
	v_pk_fma_f32 v[62:63], v[138:139], v[206:207], v[62:63] op_sel_hi:[0,1,1]
	v_pk_fma_f32 v[56:57], v[138:139], v[240:241], v[56:57] op_sel_hi:[0,1,1]
	v_pk_fma_f32 v[58:59], v[138:139], v[208:209], v[58:59] op_sel_hi:[0,1,1]
	v_mul_f32_e32 v136, v60, v60
	v_mul_f32_e32 v137, v56, v56
	v_fmac_f32_e32 v136, v61, v61
	v_fmac_f32_e32 v137, v57, v57
	v_fmac_f32_e32 v136, v62, v62
	v_fmac_f32_e32 v137, v58, v58
	v_fmac_f32_e32 v136, v63, v63
	v_fmac_f32_e32 v137, v59, v59
	v_cvt_pk_bf16_f32 v192, v60, v61
	v_cvt_pk_bf16_f32 v193, v62, v63
	v_cvt_pk_bf16_f32 v194, v56, v57
	v_cvt_pk_bf16_f32 v195, v58, v59
	v_add_f32_e32 v136, v136, v137
	v_mov_b32_e32 v63, v136
	v_add_u32_e32 v139, 0x40000, v158
	global_store_dwordx4 v139, v[192:195], s[36:37]
	s_waitcnt vmcnt(14)
	v_lshlrev_b32_e32 v238, 16, v210
	v_and_b32_e32 v239, 0xffff0000, v210
	v_lshlrev_b32_e32 v210, 16, v211
	v_and_b32_e32 v211, 0xffff0000, v211
	v_lshlrev_b32_e32 v240, 16, v212
	v_and_b32_e32 v241, 0xffff0000, v212
	v_lshlrev_b32_e32 v212, 16, v213
	v_and_b32_e32 v213, 0xffff0000, v213
	v_pk_mul_f32 v[238:239], v[184:185], v[238:239]
	v_pk_mul_f32 v[210:211], v[186:187], v[210:211]
	v_pk_mul_f32 v[240:241], v[188:189], v[240:241]
	v_pk_mul_f32 v[212:213], v[190:191], v[212:213]
	v_pk_fma_f32 v[52:53], v[138:139], v[238:239], v[52:53] op_sel_hi:[0,1,1]
	v_pk_fma_f32 v[54:55], v[138:139], v[210:211], v[54:55] op_sel_hi:[0,1,1]
	v_pk_fma_f32 v[48:49], v[138:139], v[240:241], v[48:49] op_sel_hi:[0,1,1]
	v_pk_fma_f32 v[50:51], v[138:139], v[212:213], v[50:51] op_sel_hi:[0,1,1]
	v_mul_f32_e32 v136, v52, v52
	v_mul_f32_e32 v137, v48, v48
	v_fmac_f32_e32 v136, v53, v53
	v_fmac_f32_e32 v137, v49, v49
	v_fmac_f32_e32 v136, v54, v54
	v_fmac_f32_e32 v137, v50, v50
	v_fmac_f32_e32 v136, v55, v55
	v_fmac_f32_e32 v137, v51, v51
	v_cvt_pk_bf16_f32 v198, v52, v53
	v_cvt_pk_bf16_f32 v199, v54, v55
	v_cvt_pk_bf16_f32 v200, v48, v49
	v_cvt_pk_bf16_f32 v201, v50, v51
	v_add_f32_e32 v136, v136, v137
	v_add_f32_e32 v63, v63, v136
	v_add_u32_e32 v139, 0x40000, v158
	global_store_dwordx4 v139, v[198:201], s[36:37] offset:256
	s_waitcnt vmcnt(13)
	v_mov_b32_e32 v138, v133
	v_lshlrev_b32_e32 v238, 16, v214
	v_and_b32_e32 v239, 0xffff0000, v214
	v_lshlrev_b32_e32 v214, 16, v215
	v_and_b32_e32 v215, 0xffff0000, v215
	v_lshlrev_b32_e32 v240, 16, v216
	v_and_b32_e32 v241, 0xffff0000, v216
	v_lshlrev_b32_e32 v216, 16, v217
	v_and_b32_e32 v217, 0xffff0000, v217
	v_pk_mul_f32 v[238:239], v[176:177], v[238:239]
	v_pk_mul_f32 v[214:215], v[178:179], v[214:215]
	v_pk_mul_f32 v[240:241], v[180:181], v[240:241]
	v_pk_mul_f32 v[216:217], v[182:183], v[216:217]
	v_pk_fma_f32 v[44:45], v[138:139], v[238:239], v[44:45] op_sel_hi:[0,1,1]
	v_pk_fma_f32 v[46:47], v[138:139], v[214:215], v[46:47] op_sel_hi:[0,1,1]
	v_pk_fma_f32 v[40:41], v[138:139], v[240:241], v[40:41] op_sel_hi:[0,1,1]
	v_pk_fma_f32 v[42:43], v[138:139], v[216:217], v[42:43] op_sel_hi:[0,1,1]
	v_mul_f32_e32 v136, v44, v44
	v_mul_f32_e32 v137, v40, v40
	v_fmac_f32_e32 v136, v45, v45
	v_fmac_f32_e32 v137, v41, v41
	v_fmac_f32_e32 v136, v46, v46
	v_fmac_f32_e32 v137, v42, v42
	v_fmac_f32_e32 v136, v47, v47
	v_fmac_f32_e32 v137, v43, v43
	v_cvt_pk_bf16_f32 v192, v44, v45
	v_cvt_pk_bf16_f32 v193, v46, v47
	v_cvt_pk_bf16_f32 v194, v40, v41
	v_cvt_pk_bf16_f32 v195, v42, v43
	v_add_f32_e32 v136, v136, v137
	v_mov_b32_e32 v47, v136
	v_add_u32_e32 v139, 0x48000, v158
	global_store_dwordx4 v139, v[192:195], s[36:37]
	s_waitcnt vmcnt(12)
	v_lshlrev_b32_e32 v238, 16, v218
	v_and_b32_e32 v239, 0xffff0000, v218
	v_lshlrev_b32_e32 v218, 16, v219
	v_and_b32_e32 v219, 0xffff0000, v219
	v_lshlrev_b32_e32 v240, 16, v220
	v_and_b32_e32 v241, 0xffff0000, v220
	v_lshlrev_b32_e32 v220, 16, v221
	v_and_b32_e32 v221, 0xffff0000, v221
	v_pk_mul_f32 v[238:239], v[184:185], v[238:239]
	v_pk_mul_f32 v[218:219], v[186:187], v[218:219]
	v_pk_mul_f32 v[240:241], v[188:189], v[240:241]
	v_pk_mul_f32 v[220:221], v[190:191], v[220:221]
	v_pk_fma_f32 v[36:37], v[138:139], v[238:239], v[36:37] op_sel_hi:[0,1,1]
	v_pk_fma_f32 v[38:39], v[138:139], v[218:219], v[38:39] op_sel_hi:[0,1,1]
	v_pk_fma_f32 v[32:33], v[138:139], v[240:241], v[32:33] op_sel_hi:[0,1,1]
	v_pk_fma_f32 v[34:35], v[138:139], v[220:221], v[34:35] op_sel_hi:[0,1,1]
	v_mul_f32_e32 v136, v36, v36
	v_mul_f32_e32 v137, v32, v32
	v_fmac_f32_e32 v136, v37, v37
	v_fmac_f32_e32 v137, v33, v33
	v_fmac_f32_e32 v136, v38, v38
	v_fmac_f32_e32 v137, v34, v34
	v_fmac_f32_e32 v136, v39, v39
	v_fmac_f32_e32 v137, v35, v35
	v_cvt_pk_bf16_f32 v198, v36, v37
	v_cvt_pk_bf16_f32 v199, v38, v39
	v_cvt_pk_bf16_f32 v200, v32, v33
	v_cvt_pk_bf16_f32 v201, v34, v35
	v_add_f32_e32 v136, v136, v137
	v_add_f32_e32 v47, v47, v136
	v_add_u32_e32 v139, 0x48000, v158
	global_store_dwordx4 v139, v[198:201], s[36:37] offset:256
	s_waitcnt vmcnt(11)
	v_mov_b32_e32 v138, v134
	v_lshlrev_b32_e32 v238, 16, v222
	v_and_b32_e32 v239, 0xffff0000, v222
	v_lshlrev_b32_e32 v222, 16, v223
	v_and_b32_e32 v223, 0xffff0000, v223
	v_lshlrev_b32_e32 v240, 16, v224
	v_and_b32_e32 v241, 0xffff0000, v224
	v_lshlrev_b32_e32 v224, 16, v225
	v_and_b32_e32 v225, 0xffff0000, v225
	v_pk_mul_f32 v[238:239], v[176:177], v[238:239]
	v_pk_mul_f32 v[222:223], v[178:179], v[222:223]
	v_pk_mul_f32 v[240:241], v[180:181], v[240:241]
	v_pk_mul_f32 v[224:225], v[182:183], v[224:225]
	v_pk_fma_f32 v[28:29], v[138:139], v[238:239], v[28:29] op_sel_hi:[0,1,1]
	v_pk_fma_f32 v[30:31], v[138:139], v[222:223], v[30:31] op_sel_hi:[0,1,1]
	v_pk_fma_f32 v[24:25], v[138:139], v[240:241], v[24:25] op_sel_hi:[0,1,1]
	v_pk_fma_f32 v[26:27], v[138:139], v[224:225], v[26:27] op_sel_hi:[0,1,1]
	v_mul_f32_e32 v136, v28, v28
	v_mul_f32_e32 v137, v24, v24
	v_fmac_f32_e32 v136, v29, v29
	v_fmac_f32_e32 v137, v25, v25
	v_fmac_f32_e32 v136, v30, v30
	v_fmac_f32_e32 v137, v26, v26
	v_fmac_f32_e32 v136, v31, v31
	v_fmac_f32_e32 v137, v27, v27
	v_cvt_pk_bf16_f32 v192, v28, v29
	v_cvt_pk_bf16_f32 v193, v30, v31
	v_cvt_pk_bf16_f32 v194, v24, v25
	v_cvt_pk_bf16_f32 v195, v26, v27
	v_add_f32_e32 v136, v136, v137
	v_mov_b32_e32 v31, v136
	v_add_u32_e32 v139, 0x50000, v158
	global_store_dwordx4 v139, v[192:195], s[36:37]
	s_waitcnt vmcnt(10)
	v_lshlrev_b32_e32 v238, 16, v226
	v_and_b32_e32 v239, 0xffff0000, v226
	v_lshlrev_b32_e32 v226, 16, v227
	v_and_b32_e32 v227, 0xffff0000, v227
	v_lshlrev_b32_e32 v240, 16, v228
	v_and_b32_e32 v241, 0xffff0000, v228
	v_lshlrev_b32_e32 v228, 16, v229
	v_and_b32_e32 v229, 0xffff0000, v229
	v_pk_mul_f32 v[238:239], v[184:185], v[238:239]
	v_pk_mul_f32 v[226:227], v[186:187], v[226:227]
	v_pk_mul_f32 v[240:241], v[188:189], v[240:241]
	v_pk_mul_f32 v[228:229], v[190:191], v[228:229]
	v_pk_fma_f32 v[20:21], v[138:139], v[238:239], v[20:21] op_sel_hi:[0,1,1]
	v_pk_fma_f32 v[22:23], v[138:139], v[226:227], v[22:23] op_sel_hi:[0,1,1]
	v_pk_fma_f32 v[16:17], v[138:139], v[240:241], v[16:17] op_sel_hi:[0,1,1]
	v_pk_fma_f32 v[18:19], v[138:139], v[228:229], v[18:19] op_sel_hi:[0,1,1]
	v_mul_f32_e32 v136, v20, v20
	v_mul_f32_e32 v137, v16, v16
	v_fmac_f32_e32 v136, v21, v21
	v_fmac_f32_e32 v137, v17, v17
	v_fmac_f32_e32 v136, v22, v22
	v_fmac_f32_e32 v137, v18, v18
	v_fmac_f32_e32 v136, v23, v23
	v_fmac_f32_e32 v137, v19, v19
	v_cvt_pk_bf16_f32 v198, v20, v21
	v_cvt_pk_bf16_f32 v199, v22, v23
	v_cvt_pk_bf16_f32 v200, v16, v17
	v_cvt_pk_bf16_f32 v201, v18, v19
	v_add_f32_e32 v136, v136, v137
	v_add_f32_e32 v31, v31, v136
	v_add_u32_e32 v139, 0x50000, v158
	global_store_dwordx4 v139, v[198:201], s[36:37] offset:256
	s_waitcnt vmcnt(9)
	v_mov_b32_e32 v138, v135
	v_lshlrev_b32_e32 v238, 16, v230
	v_and_b32_e32 v239, 0xffff0000, v230
	v_lshlrev_b32_e32 v230, 16, v231
	v_and_b32_e32 v231, 0xffff0000, v231
	v_lshlrev_b32_e32 v240, 16, v232
	v_and_b32_e32 v241, 0xffff0000, v232
	v_lshlrev_b32_e32 v232, 16, v233
	v_and_b32_e32 v233, 0xffff0000, v233
	v_pk_mul_f32 v[238:239], v[176:177], v[238:239]
	v_pk_mul_f32 v[230:231], v[178:179], v[230:231]
	v_pk_mul_f32 v[240:241], v[180:181], v[240:241]
	v_pk_mul_f32 v[232:233], v[182:183], v[232:233]
	v_pk_fma_f32 v[12:13], v[138:139], v[238:239], v[12:13] op_sel_hi:[0,1,1]
	v_pk_fma_f32 v[14:15], v[138:139], v[230:231], v[14:15] op_sel_hi:[0,1,1]
	v_pk_fma_f32 v[8:9], v[138:139], v[240:241], v[8:9] op_sel_hi:[0,1,1]
	v_pk_fma_f32 v[10:11], v[138:139], v[232:233], v[10:11] op_sel_hi:[0,1,1]
	v_mul_f32_e32 v136, v12, v12
	v_mul_f32_e32 v137, v8, v8
	v_fmac_f32_e32 v136, v13, v13
	v_fmac_f32_e32 v137, v9, v9
	v_fmac_f32_e32 v136, v14, v14
	v_fmac_f32_e32 v137, v10, v10
	v_fmac_f32_e32 v136, v15, v15
	v_fmac_f32_e32 v137, v11, v11
	v_cvt_pk_bf16_f32 v192, v12, v13
	v_cvt_pk_bf16_f32 v193, v14, v15
	v_cvt_pk_bf16_f32 v194, v8, v9
	v_cvt_pk_bf16_f32 v195, v10, v11
	v_add_f32_e32 v136, v136, v137
	v_mov_b32_e32 v15, v136
	v_add_u32_e32 v139, 0x58000, v158
	global_store_dwordx4 v139, v[192:195], s[36:37]
	s_waitcnt vmcnt(8)
	v_lshlrev_b32_e32 v238, 16, v234
	v_and_b32_e32 v239, 0xffff0000, v234
	v_lshlrev_b32_e32 v234, 16, v235
	v_and_b32_e32 v235, 0xffff0000, v235
	v_lshlrev_b32_e32 v240, 16, v236
	v_and_b32_e32 v241, 0xffff0000, v236
	v_lshlrev_b32_e32 v236, 16, v237
	v_and_b32_e32 v237, 0xffff0000, v237
	v_pk_mul_f32 v[238:239], v[184:185], v[238:239]
	v_pk_mul_f32 v[234:235], v[186:187], v[234:235]
	v_pk_mul_f32 v[240:241], v[188:189], v[240:241]
	v_pk_mul_f32 v[236:237], v[190:191], v[236:237]
	v_pk_fma_f32 v[4:5], v[138:139], v[238:239], v[4:5] op_sel_hi:[0,1,1]
	v_pk_fma_f32 v[6:7], v[138:139], v[234:235], v[6:7] op_sel_hi:[0,1,1]
	v_pk_fma_f32 v[0:1], v[138:139], v[240:241], v[0:1] op_sel_hi:[0,1,1]
	v_pk_fma_f32 v[2:3], v[138:139], v[236:237], v[2:3] op_sel_hi:[0,1,1]
	v_mul_f32_e32 v136, v4, v4
	v_mul_f32_e32 v137, v0, v0
	v_fmac_f32_e32 v136, v5, v5
	v_fmac_f32_e32 v137, v1, v1
	v_fmac_f32_e32 v136, v6, v6
	v_fmac_f32_e32 v137, v2, v2
	v_fmac_f32_e32 v136, v7, v7
	v_fmac_f32_e32 v137, v3, v3
	v_cvt_pk_bf16_f32 v198, v4, v5
	v_cvt_pk_bf16_f32 v199, v6, v7
	v_cvt_pk_bf16_f32 v200, v0, v1
	v_cvt_pk_bf16_f32 v201, v2, v3
	v_add_f32_e32 v136, v136, v137
	v_add_f32_e32 v15, v15, v136
	v_add_u32_e32 v139, 0x58000, v158
	global_store_dwordx4 v139, v[198:201], s[36:37] offset:256
	ds_bpermute_b32 v206, v163, v127
	ds_bpermute_b32 v207, v163, v111
	ds_bpermute_b32 v208, v163, v95
	ds_bpermute_b32 v209, v163, v79
	ds_bpermute_b32 v210, v163, v63
	ds_bpermute_b32 v211, v163, v47
	ds_bpermute_b32 v212, v163, v31
	ds_bpermute_b32 v213, v163, v15
	s_waitcnt lgkmcnt(0)
	v_add_f32_e32 v127, v127, v206
	v_add_f32_e32 v111, v111, v207
	v_add_f32_e32 v95, v95, v208
	v_add_f32_e32 v79, v79, v209
	v_add_f32_e32 v63, v63, v210
	v_add_f32_e32 v47, v47, v211
	v_add_f32_e32 v31, v31, v212
	v_add_f32_e32 v15, v15, v213
	ds_bpermute_b32 v206, v164, v127
	ds_bpermute_b32 v207, v164, v111
	ds_bpermute_b32 v208, v164, v95
	ds_bpermute_b32 v209, v164, v79
	ds_bpermute_b32 v210, v164, v63
	ds_bpermute_b32 v211, v164, v47
	ds_bpermute_b32 v212, v164, v31
	ds_bpermute_b32 v213, v164, v15
	s_waitcnt lgkmcnt(0)
	v_add_f32_e32 v127, v127, v206
	v_add_f32_e32 v111, v111, v207
	v_add_f32_e32 v95, v95, v208
	v_add_f32_e32 v79, v79, v209
	v_add_f32_e32 v63, v63, v210
	v_add_f32_e32 v47, v47, v211
	v_add_f32_e32 v31, v31, v212
	v_add_f32_e32 v15, v15, v213
	s_and_saveexec_b64 s[12:13], s[8:9]
	global_store_dword v161, v127, s[60:61]
	global_store_dword v161, v111, s[60:61] offset:1024
	global_store_dword v161, v95, s[60:61] offset:2048
	global_store_dword v161, v79, s[60:61] offset:3072
	global_store_dword v162, v63, s[60:61]
	global_store_dword v162, v47, s[60:61] offset:1024
	global_store_dword v162, v31, s[60:61] offset:2048
	global_store_dword v162, v15, s[60:61] offset:3072
	s_or_b64 exec, exec, s[12:13]
	s_andn2_b64 vcc, exec, s[10:11]
	s_mov_b64 s[0:1], -1
	s_cbranch_vccnz .LBB0_251
	s_andn2_b64 vcc, exec, s[64:65]
	s_cbranch_vccnz .LBB0_250
	s_barrier
	s_branch .LBB0_250
